# H + attention QK section keeps two d-steps of K fragments in flight (second set in v[120:127]) + first-tile K reads issued right after the pair barrier
# speedup vs baseline: 1.0052x; 1.0052x over previous
.LBB0_3761:
	s_add_i32 s0, s51, 2
	s_sub_i32 s1, s0, s48
	s_min_u32 s2, s0, s1
	s_lshl_b64 s[0:1], s[2:3], 13
	v_lshl_add_u64 v[14:15], v[180:181], 0, s[0:1]
	v_lshl_add_u64 v[218:219], v[182:183], 0, s[0:1]
	s_mov_b32 m0, s70
	s_nop 0
	global_load_lds_dwordx4 v[14:15], off
	s_add_i32 m0, s70, 0x2000
	s_nop 0
	global_load_lds_dwordx4 v[218:219], off
	s_add_i32 s0, s51, 3
	s_sub_i32 s1, s0, s48
	s_min_u32 s2, s0, s1
	s_lshl_b64 s[0:1], s[2:3], 13
	v_lshl_add_u64 v[14:15], v[180:181], 0, s[0:1]
	v_lshl_add_u64 v[218:219], v[182:183], 0, s[0:1]
	s_add_i32 m0, s70, 0x4000
	s_nop 0
	global_load_lds_dwordx4 v[14:15], off
	s_add_i32 m0, s70, 0x6000
	s_nop 0
	global_load_lds_dwordx4 v[218:219], off
	s_cmp_gt_u32 s51, s47
	s_cbranch_scc1 .LBB0_3765
	ds_read_b128 v[120:123], v200 offset:2048
	ds_read_b128 v[124:127], v200 offset:2560
	v_lshrrev_b32_e32 v1, v160, v152
	v_lshrrev_b32_e32 v14, v160, v153
	v_bitop3_b32 v228, v1, s27, v1 bitop3:0xc
	v_bitop3_b32 v229, v1, s28, v1 bitop3:0xc
	v_bitop3_b32 v230, v1, s29, v1 bitop3:0xc
	v_bitop3_b32 v231, v1, s30, v1 bitop3:0xc
	s_waitcnt lgkmcnt(3)
	v_mfma_f32_32x32x16_bf16 v[80:95], v[6:9], v[144:147], v[64:79]
	v_mul_u32_u24_e32 v228, 0xf000, v228
	v_mul_u32_u24_e32 v229, 0x7800, v229
	v_mul_u32_u24_e32 v230, 0x3c00, v230
	v_mul_u32_u24_e32 v231, 0x1e00, v231
	s_waitcnt lgkmcnt(2)
	v_mfma_f32_32x32x16_bf16 v[96:111], v[10:13], v[144:147], v[64:79]
	ds_read_b128 v[6:9], v200 offset:4096
	ds_read_b128 v[10:13], v200 offset:4608
	v_bitop3_b32 v232, v14, s27, v14 bitop3:0xc
	v_bitop3_b32 v233, v14, s28, v14 bitop3:0xc
	v_bitop3_b32 v234, v14, s29, v14 bitop3:0xc
	v_bitop3_b32 v235, v14, s30, v14 bitop3:0xc
	v_mul_u32_u24_e32 v232, 0xf000, v232
	v_mul_u32_u24_e32 v233, 0x7800, v233
	v_mul_u32_u24_e32 v234, 0x3c00, v234
	v_mul_u32_u24_e32 v235, 0x1e00, v235
	s_waitcnt lgkmcnt(3)
	v_mfma_f32_32x32x16_bf16 v[80:95], v[120:123], v[136:139], v[80:95]
	v_bitop3_b32 v236, v1, s31, v1 bitop3:0xc
	v_bitop3_b32 v237, v1, s33, v1 bitop3:0xc
	v_bitop3_b32 v238, v1, s34, v1 bitop3:0xc
	v_bitop3_b32 v239, v1, s35, v1 bitop3:0xc
	s_waitcnt lgkmcnt(2)
	v_mfma_f32_32x32x16_bf16 v[96:111], v[124:127], v[136:139], v[96:111]
	ds_read_b128 v[120:123], v200 offset:6144
	ds_read_b128 v[124:127], v200 offset:6656
	v_mul_u32_u24_e32 v236, 0xf00, v236
	v_mul_u32_u24_e32 v237, 0x780, v237
	v_mul_u32_u24_e32 v238, 0x3c0, v238
	v_mul_u32_u24_e32 v239, 0x1e0, v239
	v_bitop3_b32 v224, v14, s31, v14 bitop3:0xc
	v_bitop3_b32 v225, v14, s33, v14 bitop3:0xc
	v_bitop3_b32 v226, v14, s34, v14 bitop3:0xc
	v_bitop3_b32 v227, v14, s35, v14 bitop3:0xc
	s_waitcnt lgkmcnt(3)
	v_mfma_f32_32x32x16_bf16 v[80:95], v[6:9], v[140:143], v[80:95]
	v_mul_u32_u24_e32 v224, 0xf00, v224
	v_mul_u32_u24_e32 v225, 0x780, v225
	v_mul_u32_u24_e32 v226, 0x3c0, v226
	v_mul_u32_u24_e32 v227, 0x1e0, v227
	s_waitcnt lgkmcnt(2)
	v_mfma_f32_32x32x16_bf16 v[96:111], v[10:13], v[140:143], v[96:111]
	s_xor_b64 s[4:5], s[20:21], -1
	s_waitcnt lgkmcnt(1)
	v_mfma_f32_32x32x16_bf16 v[80:95], v[120:123], v[148:151], v[80:95]
	s_waitcnt lgkmcnt(0)
	v_mfma_f32_32x32x16_bf16 v[96:111], v[124:127], v[148:151], v[96:111]
	v_mfma_f32_32x32x16_bf16 v[80:95], v[112:115], v[228:231], v[80:95]
	v_mfma_f32_32x32x16_bf16 v[96:111], v[112:115], v[232:235], v[96:111]
	v_mfma_f32_32x32x16_bf16 v[80:95], v[116:119], v[236:239], v[80:95]
	v_mfma_f32_32x32x16_bf16 v[96:111], v[116:119], v[224:227], v[96:111]
	s_nop 15
	s_nop 7
	v_max3_f32 v1, v80, v81, v82
	v_max3_f32 v6, v83, v84, v85
	v_max3_f32 v1, v1, v86, v87
	v_max3_f32 v6, v6, v88, v89
	v_max3_f32 v1, v1, v90, v91
	v_max3_f32 v6, v6, v92, v93
	v_max3_f32 v1, v1, v94, v95
	v_max_f32 v1, v1, v6
	s_nop 0
	v_max3_f32 v7, v96, v97, v98
	v_max3_f32 v6, v99, v100, v101
	v_max3_f32 v7, v7, v102, v103
	v_max3_f32 v6, v6, v104, v105
	v_max3_f32 v7, v7, v106, v107
	v_max3_f32 v6, v6, v108, v109
	v_max3_f32 v7, v7, v110, v111
	v_max3_f32 v7, v7, v6, v1
	s_nop 0
	v_mov_b32_e32 v1, v7
	s_nop 1
	v_permlane32_swap_b32_e32 v7, v1
	v_max_f32_e32 v1, v1, v1
	v_max_f32_e32 v6, v7, v7
	v_max_f32_e32 v1, v6, v1
	v_cmp_lt_f32_e64 s[0:1], s36, v1
	s_and_b64 s[10:11], s[0:1], s[4:5]
	v_cmp_lt_f32_e32 vcc, s37, v1
	s_or_b64 s[4:5], vcc, s[10:11]
	v_cndmask_b32_e64 v6, 0, 1, s[4:5]
	v_cmp_ne_u32_e32 vcc, 0, v6
	s_cbranch_vccz .LBB0_3764
	v_cndmask_b32_e64 v6, 0, v1, s[4:5]
	v_exp_f32_e64 v1, -v6
	v_add_f32_e32 v171, v171, v6
	s_or_b64 s[0:1], s[20:21], s[0:1]
	v_xor_b32_e32 v64, 0x80000000, v171
	v_cndmask_b32_e64 v8, v1, 1.0, s[10:11]
	s_andn2_b64 s[4:5], s[20:21], exec
	s_and_b64 s[0:1], s[0:1], exec
	v_pk_add_f32 v[80:81], v[80:81], v[6:7] op_sel_hi:[1,0] neg_lo:[0,1] neg_hi:[0,1]
	v_pk_add_f32 v[96:97], v[96:97], v[6:7] op_sel_hi:[1,0] neg_lo:[0,1] neg_hi:[0,1]
	v_pk_add_f32 v[82:83], v[82:83], v[6:7] op_sel_hi:[1,0] neg_lo:[0,1] neg_hi:[0,1]
	v_pk_add_f32 v[98:99], v[98:99], v[6:7] op_sel_hi:[1,0] neg_lo:[0,1] neg_hi:[0,1]
	v_pk_add_f32 v[84:85], v[84:85], v[6:7] op_sel_hi:[1,0] neg_lo:[0,1] neg_hi:[0,1]
	v_pk_add_f32 v[100:101], v[100:101], v[6:7] op_sel_hi:[1,0] neg_lo:[0,1] neg_hi:[0,1]
	v_pk_add_f32 v[86:87], v[86:87], v[6:7] op_sel_hi:[1,0] neg_lo:[0,1] neg_hi:[0,1]
	v_pk_add_f32 v[102:103], v[102:103], v[6:7] op_sel_hi:[1,0] neg_lo:[0,1] neg_hi:[0,1]
	v_pk_add_f32 v[88:89], v[88:89], v[6:7] op_sel_hi:[1,0] neg_lo:[0,1] neg_hi:[0,1]
	v_pk_add_f32 v[104:105], v[104:105], v[6:7] op_sel_hi:[1,0] neg_lo:[0,1] neg_hi:[0,1]
	v_pk_add_f32 v[90:91], v[90:91], v[6:7] op_sel_hi:[1,0] neg_lo:[0,1] neg_hi:[0,1]
	v_pk_add_f32 v[106:107], v[106:107], v[6:7] op_sel_hi:[1,0] neg_lo:[0,1] neg_hi:[0,1]
	v_pk_add_f32 v[92:93], v[92:93], v[6:7] op_sel_hi:[1,0] neg_lo:[0,1] neg_hi:[0,1]
	v_pk_add_f32 v[108:109], v[108:109], v[6:7] op_sel_hi:[1,0] neg_lo:[0,1] neg_hi:[0,1]
	v_pk_add_f32 v[94:95], v[94:95], v[6:7] op_sel_hi:[1,0] neg_lo:[0,1] neg_hi:[0,1]
	v_pk_add_f32 v[110:111], v[110:111], v[6:7] op_sel_hi:[1,0] neg_lo:[0,1] neg_hi:[0,1]
	v_mov_b32_e32 v65, v64
	v_mov_b32_e32 v66, v64
	v_mov_b32_e32 v67, v64
	v_mov_b32_e32 v68, v64
	v_mov_b32_e32 v69, v64
	v_mov_b32_e32 v70, v64
	v_mov_b32_e32 v71, v64
	v_mov_b32_e32 v72, v64
	v_mov_b32_e32 v73, v64
	v_mov_b32_e32 v74, v64
	v_mov_b32_e32 v75, v64
	v_mov_b32_e32 v76, v64
	v_mov_b32_e32 v77, v64
	v_mov_b32_e32 v78, v64
	v_mov_b32_e32 v79, v64
	v_pk_mul_f32 v[30:31], v[30:31], v[8:9] op_sel_hi:[1,0]
	v_pk_mul_f32 v[28:29], v[28:29], v[8:9] op_sel_hi:[1,0]
	v_pk_mul_f32 v[26:27], v[26:27], v[8:9] op_sel_hi:[1,0]
	v_pk_mul_f32 v[24:25], v[24:25], v[8:9] op_sel_hi:[1,0]
	v_pk_mul_f32 v[22:23], v[22:23], v[8:9] op_sel_hi:[1,0]
	v_pk_mul_f32 v[20:21], v[20:21], v[8:9] op_sel_hi:[1,0]
	v_pk_mul_f32 v[18:19], v[18:19], v[8:9] op_sel_hi:[1,0]
	v_pk_mul_f32 v[16:17], v[16:17], v[8:9] op_sel_hi:[1,0]
	v_pk_mul_f32 v[46:47], v[46:47], v[8:9] op_sel_hi:[1,0]
	v_pk_mul_f32 v[44:45], v[44:45], v[8:9] op_sel_hi:[1,0]
	v_pk_mul_f32 v[42:43], v[42:43], v[8:9] op_sel_hi:[1,0]
	v_pk_mul_f32 v[40:41], v[40:41], v[8:9] op_sel_hi:[1,0]
	v_pk_mul_f32 v[38:39], v[38:39], v[8:9] op_sel_hi:[1,0]
	v_pk_mul_f32 v[36:37], v[36:37], v[8:9] op_sel_hi:[1,0]
	v_pk_mul_f32 v[34:35], v[34:35], v[8:9] op_sel_hi:[1,0]
	v_pk_mul_f32 v[32:33], v[32:33], v[8:9] op_sel_hi:[1,0]
	v_pk_mul_f32 v[62:63], v[62:63], v[8:9] op_sel_hi:[1,0]
	v_pk_mul_f32 v[60:61], v[60:61], v[8:9] op_sel_hi:[1,0]
	v_pk_mul_f32 v[58:59], v[58:59], v[8:9] op_sel_hi:[1,0]
	v_pk_mul_f32 v[56:57], v[56:57], v[8:9] op_sel_hi:[1,0]
	v_pk_mul_f32 v[54:55], v[54:55], v[8:9] op_sel_hi:[1,0]
	v_pk_mul_f32 v[52:53], v[52:53], v[8:9] op_sel_hi:[1,0]
	v_pk_mul_f32 v[50:51], v[50:51], v[8:9] op_sel_hi:[1,0]
	v_pk_mul_f32 v[48:49], v[48:49], v[8:9] op_sel_hi:[1,0]
	s_or_b64 s[20:21], s[4:5], s[0:1]

; __device__ __forceinline__ float max32raw(const f32x16& a, const f32x16& b) {
;     float x, y;
;     asm volatile("s_nop 15\n\ts_nop 7\n\t"
;         "v_max3_f32 %0, %2, %3, %4\n\tv_max3_f32 %1, %5, %6, %7\n\t"
;         "v_max3_f32 %0, %0, %8, %9\n\tv_max3_f32 %1, %1, %10, %11\n\t"
;         "v_max3_f32 %0, %0, %12, %13\n\tv_max3_f32 %1, %1, %14, %15\n\t"
;         "v_max3_f32 %0, %0, %16, %17\n\tv_max_f32 %0, %0, %1"
;         : "=&v"(x), "=&v"(y)
;         : "v"(a[0]), "v"(a[1]), "v"(a[2]), "v"(a[3]), "v"(a[4]), "v"(a[5]), "v"(a[6]), "v"(a[7]), "v"(a[8]), "v"(a[9]), "v"(a[10]), "v"(a[11]), "v"(a[12]), "v"(a[13]), "v"(a[14]), "v"(a[15]));
;     float u, v;
;     asm volatile("v_max3_f32 %0, %2, %3, %4\n\tv_max3_f32 %1, %5, %6, %7\n\t"
;         "v_max3_f32 %0, %0, %8, %9\n\tv_max3_f32 %1, %1, %10, %11\n\t"
;         "v_max3_f32 %0, %0, %12, %13\n\tv_max3_f32 %1, %1, %14, %15\n\t"
;         "v_max3_f32 %0, %0, %16, %17\n\tv_max3_f32 %0, %0, %1, %18"
;         : "=&v"(u), "=&v"(v)
;         : "v"(b[0]), "v"(b[1]), "v"(b[2]), "v"(b[3]), "v"(b[4]), "v"(b[5]), "v"(b[6]), "v"(b[7]), "v"(b[8]), "v"(b[9]), "v"(b[10]), "v"(b[11]), "v"(b[12]), "v"(b[13]), "v"(b[14]), "v"(b[15]), "v"(x));
;     return u;
; }
.LBB0_3765:
	s_cmp_ge_u32 s51, s47
	s_cbranch_scc1 .LBB0_3770
	ds_read_b128 v[6:9], v200 offset:16384
	ds_read_b128 v[10:13], v200 offset:16896
	ds_read_b128 v[120:123], v200 offset:18432
	ds_read_b128 v[124:127], v200 offset:18944
	v_lshrrev_b32_e32 v1, v160, v154
	v_lshrrev_b32_e32 v14, v160, v155
	v_bitop3_b32 v228, v1, s27, v1 bitop3:0xc
	v_bitop3_b32 v229, v1, s28, v1 bitop3:0xc
	v_bitop3_b32 v230, v1, s29, v1 bitop3:0xc
	v_bitop3_b32 v231, v1, s30, v1 bitop3:0xc
	s_waitcnt lgkmcnt(3)
	v_mfma_f32_32x32x16_bf16 v[80:95], v[6:9], v[144:147], v[64:79]
	v_mul_u32_u24_e32 v228, 0xf000, v228
	v_mul_u32_u24_e32 v229, 0x7800, v229
	v_mul_u32_u24_e32 v230, 0x3c00, v230
	v_mul_u32_u24_e32 v231, 0x1e00, v231
	s_waitcnt lgkmcnt(2)
	v_mfma_f32_32x32x16_bf16 v[96:111], v[10:13], v[144:147], v[64:79]
	ds_read_b128 v[6:9], v200 offset:20480
	ds_read_b128 v[10:13], v200 offset:20992
	v_bitop3_b32 v232, v14, s27, v14 bitop3:0xc
	v_bitop3_b32 v233, v14, s28, v14 bitop3:0xc
	v_bitop3_b32 v234, v14, s29, v14 bitop3:0xc
	v_bitop3_b32 v235, v14, s30, v14 bitop3:0xc
	v_mul_u32_u24_e32 v232, 0xf000, v232
	v_mul_u32_u24_e32 v233, 0x7800, v233
	v_mul_u32_u24_e32 v234, 0x3c00, v234
	v_mul_u32_u24_e32 v235, 0x1e00, v235
	s_waitcnt lgkmcnt(3)
	v_mfma_f32_32x32x16_bf16 v[80:95], v[120:123], v[136:139], v[80:95]
	v_bitop3_b32 v236, v1, s31, v1 bitop3:0xc
	v_bitop3_b32 v237, v1, s33, v1 bitop3:0xc
	v_bitop3_b32 v238, v1, s34, v1 bitop3:0xc
	v_bitop3_b32 v239, v1, s35, v1 bitop3:0xc
	s_waitcnt lgkmcnt(2)
	v_mfma_f32_32x32x16_bf16 v[96:111], v[124:127], v[136:139], v[96:111]
	ds_read_b128 v[120:123], v200 offset:22528
	ds_read_b128 v[124:127], v200 offset:23040
	v_mul_u32_u24_e32 v236, 0xf00, v236
	v_mul_u32_u24_e32 v237, 0x780, v237
	v_mul_u32_u24_e32 v238, 0x3c0, v238
	v_mul_u32_u24_e32 v239, 0x1e0, v239
	v_bitop3_b32 v224, v14, s31, v14 bitop3:0xc
	v_bitop3_b32 v225, v14, s33, v14 bitop3:0xc
	v_bitop3_b32 v226, v14, s34, v14 bitop3:0xc
	v_bitop3_b32 v227, v14, s35, v14 bitop3:0xc
	s_waitcnt lgkmcnt(3)
	v_mfma_f32_32x32x16_bf16 v[80:95], v[6:9], v[140:143], v[80:95]
	v_mul_u32_u24_e32 v224, 0xf00, v224
	v_mul_u32_u24_e32 v225, 0x780, v225
	v_mul_u32_u24_e32 v226, 0x3c0, v226
	v_mul_u32_u24_e32 v227, 0x1e0, v227
	s_waitcnt lgkmcnt(2)
	v_mfma_f32_32x32x16_bf16 v[96:111], v[10:13], v[140:143], v[96:111]
	s_xor_b64 s[4:5], s[20:21], -1
	v_cndmask_b32_e64 v1, 0, 1, s[4:5]
	v_cmp_ne_u32_e32 vcc, 0, v1
	s_waitcnt lgkmcnt(1)
	v_mfma_f32_32x32x16_bf16 v[80:95], v[120:123], v[148:151], v[80:95]
	s_waitcnt lgkmcnt(0)
	v_mfma_f32_32x32x16_bf16 v[96:111], v[124:127], v[148:151], v[96:111]
	v_mfma_f32_32x32x16_bf16 v[80:95], v[112:115], v[228:231], v[80:95]
	v_mfma_f32_32x32x16_bf16 v[96:111], v[112:115], v[232:235], v[96:111]
	v_mfma_f32_32x32x16_bf16 v[80:95], v[116:119], v[236:239], v[80:95]
	v_mfma_f32_32x32x16_bf16 v[96:111], v[116:119], v[224:227], v[96:111]
	s_cbranch_vccz .LBB0_3769
	s_nop 15
	s_nop 7
	v_max3_f32 v1, v80, v81, v82
	v_max3_f32 v6, v83, v84, v85
	v_max3_f32 v1, v1, v86, v87
	v_max3_f32 v6, v6, v88, v89
	v_max3_f32 v1, v1, v90, v91
	v_max3_f32 v6, v6, v92, v93
	v_max3_f32 v1, v1, v94, v95
	v_max_f32 v1, v1, v6
	s_nop 0
	v_max3_f32 v7, v96, v97, v98
	v_max3_f32 v6, v99, v100, v101
	v_max3_f32 v7, v7, v102, v103
	v_max3_f32 v6, v6, v104, v105
	v_max3_f32 v7, v7, v106, v107
	v_max3_f32 v6, v6, v108, v109
	v_max3_f32 v7, v7, v110, v111
	v_max3_f32 v7, v7, v6, v1
	s_nop 0
	v_mov_b32_e32 v1, v7
	s_nop 1
	v_permlane32_swap_b32_e32 v7, v1
	v_max_f32_e32 v1, v1, v1
	v_max_f32_e32 v6, v7, v7
	v_max_f32_e32 v1, v6, v1
	v_cmp_lt_f32_e64 s[0:1], s36, v1
	s_and_b64 s[10:11], s[0:1], s[4:5]
	v_cmp_lt_f32_e32 vcc, s37, v1
	s_or_b64 s[4:5], vcc, s[10:11]
	v_cndmask_b32_e64 v6, 0, 1, s[4:5]
	v_cmp_ne_u32_e32 vcc, 0, v6
	s_cbranch_vccz .LBB0_3769
	v_cndmask_b32_e64 v1, 0, v1, s[4:5]
	v_exp_f32_e64 v6, -v1
	v_add_f32_e32 v171, v171, v1
	s_or_b64 s[0:1], s[20:21], s[0:1]
	v_xor_b32_e32 v64, 0x80000000, v171
	v_cndmask_b32_e64 v6, v6, 1.0, s[10:11]
	s_andn2_b64 s[4:5], s[20:21], exec
	s_and_b64 s[0:1], s[0:1], exec
	v_mov_b32_e32 v65, v64
	v_mov_b32_e32 v66, v64
	v_mov_b32_e32 v67, v64
	v_mov_b32_e32 v68, v64
	v_mov_b32_e32 v69, v64
	v_mov_b32_e32 v70, v64
	v_mov_b32_e32 v71, v64
	v_mov_b32_e32 v72, v64
	v_mov_b32_e32 v73, v64
	v_mov_b32_e32 v74, v64
	v_mov_b32_e32 v75, v64
	v_mov_b32_e32 v76, v64
	v_mov_b32_e32 v77, v64
	v_mov_b32_e32 v78, v64
	v_mov_b32_e32 v79, v64
	v_pk_mul_f32 v[30:31], v[30:31], v[6:7] op_sel_hi:[1,0]
	v_pk_mul_f32 v[28:29], v[28:29], v[6:7] op_sel_hi:[1,0]
	v_pk_mul_f32 v[26:27], v[26:27], v[6:7] op_sel_hi:[1,0]
	v_pk_mul_f32 v[24:25], v[24:25], v[6:7] op_sel_hi:[1,0]
	v_pk_mul_f32 v[22:23], v[22:23], v[6:7] op_sel_hi:[1,0]
	v_pk_mul_f32 v[20:21], v[20:21], v[6:7] op_sel_hi:[1,0]
	v_pk_mul_f32 v[18:19], v[18:19], v[6:7] op_sel_hi:[1,0]
	v_pk_mul_f32 v[16:17], v[16:17], v[6:7] op_sel_hi:[1,0]
	v_pk_mul_f32 v[46:47], v[46:47], v[6:7] op_sel_hi:[1,0]
	v_pk_mul_f32 v[44:45], v[44:45], v[6:7] op_sel_hi:[1,0]
	v_pk_mul_f32 v[42:43], v[42:43], v[6:7] op_sel_hi:[1,0]
	v_pk_mul_f32 v[40:41], v[40:41], v[6:7] op_sel_hi:[1,0]
	v_pk_mul_f32 v[38:39], v[38:39], v[6:7] op_sel_hi:[1,0]
	v_pk_mul_f32 v[36:37], v[36:37], v[6:7] op_sel_hi:[1,0]
	v_pk_mul_f32 v[34:35], v[34:35], v[6:7] op_sel_hi:[1,0]
	v_pk_mul_f32 v[32:33], v[32:33], v[6:7] op_sel_hi:[1,0]
	v_pk_mul_f32 v[62:63], v[62:63], v[6:7] op_sel_hi:[1,0]
	v_pk_mul_f32 v[60:61], v[60:61], v[6:7] op_sel_hi:[1,0]
	v_pk_mul_f32 v[58:59], v[58:59], v[6:7] op_sel_hi:[1,0]
	v_pk_mul_f32 v[56:57], v[56:57], v[6:7] op_sel_hi:[1,0]
	v_pk_mul_f32 v[54:55], v[54:55], v[6:7] op_sel_hi:[1,0]
	v_pk_mul_f32 v[52:53], v[52:53], v[6:7] op_sel_hi:[1,0]
	v_pk_mul_f32 v[50:51], v[50:51], v[6:7] op_sel_hi:[1,0]
	v_pk_mul_f32 v[48:49], v[48:49], v[6:7] op_sel_hi:[1,0]
	v_sub_f32_e32 v95, v95, v1
	v_sub_f32_e32 v94, v94, v1
	v_sub_f32_e32 v93, v93, v1
	v_sub_f32_e32 v92, v92, v1
	v_sub_f32_e32 v91, v91, v1
	v_sub_f32_e32 v90, v90, v1
	v_sub_f32_e32 v89, v89, v1
	v_sub_f32_e32 v88, v88, v1
	v_sub_f32_e32 v87, v87, v1
	v_sub_f32_e32 v86, v86, v1
	v_sub_f32_e32 v85, v85, v1
	v_sub_f32_e32 v84, v84, v1
	v_sub_f32_e32 v83, v83, v1
	v_sub_f32_e32 v82, v82, v1
	v_sub_f32_e32 v81, v81, v1
	v_sub_f32_e32 v80, v80, v1
	v_sub_f32_e32 v111, v111, v1
	v_sub_f32_e32 v110, v110, v1
	v_sub_f32_e32 v109, v109, v1
	v_sub_f32_e32 v108, v108, v1
	v_sub_f32_e32 v107, v107, v1
	v_sub_f32_e32 v106, v106, v1
	v_sub_f32_e32 v105, v105, v1
	v_sub_f32_e32 v104, v104, v1
	v_sub_f32_e32 v103, v103, v1
	v_sub_f32_e32 v102, v102, v1
	v_sub_f32_e32 v101, v101, v1
	v_sub_f32_e32 v100, v100, v1
	v_sub_f32_e32 v99, v99, v1
	v_sub_f32_e32 v98, v98, v1
	v_sub_f32_e32 v97, v97, v1
	v_sub_f32_e32 v96, v96, v1
	s_or_b64 s[20:21], s[4:5], s[0:1]
